# grid barrier: non-leader workgroups spin on the top-level generation word directly (one release hop fewer)
# baseline (speedup 1.0000x reference)
.LBB0_762:
	s_or_b64 exec, exec, s[2:3]
	v_cvt_f32_u32_e32 v6, v4
	s_waitcnt vmcnt(0)
	v_readfirstlane_b32 s2, v5
	v_sub_u32_e32 v5, 0, v4
	v_rcp_iflag_f32_e32 v6, v6
	v_add_u32_e32 v7, s2, v3
	v_mul_f32_e32 v6, 0x4f7ffffe, v6
	v_cvt_u32_f32_e32 v6, v6
	v_mul_lo_u32 v3, v5, v6
	v_mul_hi_u32 v3, v6, v3
	v_add_u32_e32 v3, v6, v3
	v_mul_hi_u32 v3, v7, v3
	v_mul_lo_u32 v5, v3, v4
	v_sub_u32_e32 v5, v7, v5
	v_add_u32_e32 v6, 1, v3
	v_cmp_ge_u32_e32 vcc, v5, v4
	s_nop 1
	v_cndmask_b32_e32 v3, v3, v6, vcc
	v_sub_u32_e32 v6, v5, v4
	v_cndmask_b32_e32 v5, v5, v6, vcc
	v_add_u32_e32 v6, 1, v3
	v_cmp_ge_u32_e32 vcc, v5, v4
	v_add_u32_e32 v5, 1, v7
	s_nop 0
	v_cndmask_b32_e32 v3, v3, v6, vcc
	v_mul_lo_u32 v6, v4, v3
	v_add_u32_e32 v4, v6, v4
	v_cmp_ne_u32_e32 vcc, v5, v4
	s_and_saveexec_b64 s[2:3], vcc
	s_xor_b64 s[2:3], exec, s[2:3]
	s_cbranch_execz .LBB0_776
	v_readlane_b32 s16, v244, 3
	v_readlane_b32 s17, v244, 4
	s_waitcnt lgkmcnt(0)
	s_nop 3
	global_load_dword v2, v34, s[16:17] sc1
	s_waitcnt vmcnt(0)
	v_cmp_eq_u32_e32 vcc, v2, v3
	s_and_saveexec_b64 s[16:17], vcc
	s_cbranch_execz .LBB0_775
	s_mov_b32 s24, 1
	s_mov_b64 s[18:19], 0
	s_branch .LBB0_766

.LBB0_768:
	v_readlane_b32 s28, v244, 3
	v_readlane_b32 s29, v244, 4
	s_add_i32 s24, s24, 1
	s_mov_b64 s[30:31], -1
	s_nop 2
	global_load_dword v2, v34, s[28:29] sc1
	s_waitcnt vmcnt(0)
	v_cmp_ne_u32_e32 vcc, v2, v3
	s_orn2_b64 s[28:29], vcc, exec
	s_branch .LBB0_765
